# cumulative work-removal stack: v168 + exp row-sum by packed adds (4 MLA sites, padded) + v_mov_b64 accumulator zero-init (4 GEMM preheaders)
# speedup vs baseline: 1.0036x; 1.0036x over previous
.LBB0_367:
	v_exp_f32_e32 v218, v80
	v_exp_f32_e32 v219, v81
	v_exp_f32_e32 v220, v82
	v_exp_f32_e32 v221, v83
	v_exp_f32_e32 v222, v84
	v_exp_f32_e32 v223, v85
	v_exp_f32_e32 v224, v86
	v_exp_f32_e32 v225, v87
	v_cvt_pk_bf16_f32 v8, v218, v219
	v_cvt_pk_bf16_f32 v9, v220, v221
	v_cvt_pk_bf16_f32 v10, v222, v223
	v_cvt_pk_bf16_f32 v11, v224, v225
	v_pk_add_f32 v[226:227], v[218:219], v[220:221]
	v_pk_add_f32 v[226:227], v[226:227], v[222:223]
	v_pk_add_f32 v[226:227], v[226:227], v[224:225]
	v_exp_f32_e32 v218, v88
	v_exp_f32_e32 v219, v89
	v_exp_f32_e32 v220, v90
	v_exp_f32_e32 v221, v91
	v_exp_f32_e32 v222, v92
	v_exp_f32_e32 v223, v93
	v_exp_f32_e32 v224, v94
	v_exp_f32_e32 v225, v95
	v_cvt_pk_bf16_f32 v18, v218, v219
	v_cvt_pk_bf16_f32 v19, v220, v221
	v_cvt_pk_bf16_f32 v20, v222, v223
	v_cvt_pk_bf16_f32 v21, v224, v225
	v_pk_add_f32 v[226:227], v[226:227], v[218:219]
	v_pk_add_f32 v[226:227], v[226:227], v[220:221]
	v_pk_add_f32 v[226:227], v[226:227], v[222:223]
	v_pk_add_f32 v[226:227], v[226:227], v[224:225]
	v_exp_f32_e32 v218, v96
	v_exp_f32_e32 v219, v97
	v_exp_f32_e32 v220, v98
	v_exp_f32_e32 v221, v99
	v_exp_f32_e32 v222, v100
	v_exp_f32_e32 v223, v101
	v_exp_f32_e32 v224, v102
	v_exp_f32_e32 v225, v103
	v_cvt_pk_bf16_f32 v12, v218, v219
	v_cvt_pk_bf16_f32 v13, v220, v221
	v_cvt_pk_bf16_f32 v14, v222, v223
	v_cvt_pk_bf16_f32 v15, v224, v225
	v_pk_add_f32 v[226:227], v[226:227], v[218:219]
	v_pk_add_f32 v[226:227], v[226:227], v[220:221]
	v_pk_add_f32 v[226:227], v[226:227], v[222:223]
	v_pk_add_f32 v[226:227], v[226:227], v[224:225]
	v_exp_f32_e32 v218, v104
	v_exp_f32_e32 v219, v105
	v_exp_f32_e32 v220, v106
	v_exp_f32_e32 v221, v107
	v_exp_f32_e32 v222, v108
	v_exp_f32_e32 v223, v109
	v_exp_f32_e32 v224, v110
	v_exp_f32_e32 v225, v111
	v_cvt_pk_bf16_f32 v22, v218, v219
	v_cvt_pk_bf16_f32 v23, v220, v221
	v_cvt_pk_bf16_f32 v24, v222, v223
	v_cvt_pk_bf16_f32 v25, v224, v225
	v_pk_add_f32 v[226:227], v[226:227], v[218:219]
	v_pk_add_f32 v[226:227], v[226:227], v[220:221]
	v_pk_add_f32 v[226:227], v[226:227], v[222:223]
	v_pk_add_f32 v[226:227], v[226:227], v[224:225]
	v_add_u32_e32 v0, 0xd000, v2
	s_waitcnt lgkmcnt(2)
	v_mfma_f32_32x32x16_bf16 v[48:63], v[182:185], v[8:11], v[48:63]
	ds_read_b64_tr_b16 v[26:27], v0 offset:12288
	ds_read_b64_tr_b16 v[28:29], v0 offset:12800
	ds_read_b64_tr_b16 v[84:85], v0 offset:13312
	ds_read_b64_tr_b16 v[86:87], v0 offset:13824
	s_waitcnt lgkmcnt(2)
	v_mfma_f32_32x32x16_bf16 v[32:47], v[26:29], v[8:11], v[32:47]
	v_mfma_f32_32x32x16_bf16 v[48:63], v[186:189], v[18:21], v[48:63]
	s_waitcnt lgkmcnt(0)
	v_mfma_f32_32x32x16_bf16 v[32:47], v[84:87], v[18:21], v[32:47]
	ds_read_b64_tr_b16 v[8:9], v2 offset:63488
	ds_read_b64_tr_b16 v[10:11], v2 offset:64000
	ds_read_b64_tr_b16 v[18:19], v2 offset:64512
	ds_read_b64_tr_b16 v[20:21], v2 offset:65024
	s_waitcnt lgkmcnt(2)
	v_mfma_f32_32x32x16_bf16 v[48:63], v[8:11], v[12:15], v[48:63]
	ds_read_b64_tr_b16 v[2:3], v0 offset:14336
	ds_read_b64_tr_b16 v[4:5], v0 offset:14848
	ds_read_b64_tr_b16 v[8:9], v0 offset:15360
	ds_read_b64_tr_b16 v[10:11], v0 offset:15872
	s_waitcnt lgkmcnt(2)
	v_mfma_f32_32x32x16_bf16 v[32:47], v[2:5], v[12:15], v[32:47]
	v_mfma_f32_32x32x16_bf16 v[48:63], v[18:21], v[22:25], v[48:63]
	s_waitcnt lgkmcnt(0)
	v_mfma_f32_32x32x16_bf16 v[32:47], v[8:11], v[22:25], v[32:47]
	v_add_f32_e32 v228, v226, v227
	v_add_f32_e32 v6, v6, v228
	s_andn2_b64 vcc, exec, s[4:5]
	s_cbranch_vccnz .LBB0_350
	s_branch .LBB0_374
	s_nop 0
	s_nop 0
	s_nop 0
	s_nop 0
	s_nop 0
	s_nop 0
	s_nop 0
	s_nop 0
	s_nop 0
	s_nop 0
	s_nop 0

.LBB0_372:
	v_exp_f32_e32 v218, v80
	v_exp_f32_e32 v219, v81
	v_exp_f32_e32 v220, v82
	v_exp_f32_e32 v221, v83
	v_exp_f32_e32 v222, v84
	v_exp_f32_e32 v223, v85
	v_exp_f32_e32 v224, v86
	v_exp_f32_e32 v225, v87
	v_cvt_pk_bf16_f32 v8, v218, v219
	v_cvt_pk_bf16_f32 v9, v220, v221
	v_cvt_pk_bf16_f32 v10, v222, v223
	v_cvt_pk_bf16_f32 v11, v224, v225
	v_pk_add_f32 v[226:227], v[218:219], v[220:221]
	v_pk_add_f32 v[226:227], v[226:227], v[222:223]
	v_pk_add_f32 v[226:227], v[226:227], v[224:225]
	v_exp_f32_e32 v218, v88
	v_exp_f32_e32 v219, v89
	v_exp_f32_e32 v220, v90
	v_exp_f32_e32 v221, v91
	v_exp_f32_e32 v222, v92
	v_exp_f32_e32 v223, v93
	v_exp_f32_e32 v224, v94
	v_exp_f32_e32 v225, v95
	v_cvt_pk_bf16_f32 v18, v218, v219
	v_cvt_pk_bf16_f32 v19, v220, v221
	v_cvt_pk_bf16_f32 v20, v222, v223
	v_cvt_pk_bf16_f32 v21, v224, v225
	v_pk_add_f32 v[226:227], v[226:227], v[218:219]
	v_pk_add_f32 v[226:227], v[226:227], v[220:221]
	v_pk_add_f32 v[226:227], v[226:227], v[222:223]
	v_pk_add_f32 v[226:227], v[226:227], v[224:225]
	v_exp_f32_e32 v218, v96
	v_exp_f32_e32 v219, v97
	v_exp_f32_e32 v220, v98
	v_exp_f32_e32 v221, v99
	v_exp_f32_e32 v222, v100
	v_exp_f32_e32 v223, v101
	v_exp_f32_e32 v224, v102
	v_exp_f32_e32 v225, v103
	v_cvt_pk_bf16_f32 v12, v218, v219
	v_cvt_pk_bf16_f32 v13, v220, v221
	v_cvt_pk_bf16_f32 v14, v222, v223
	v_cvt_pk_bf16_f32 v15, v224, v225
	v_pk_add_f32 v[226:227], v[226:227], v[218:219]
	v_pk_add_f32 v[226:227], v[226:227], v[220:221]
	v_pk_add_f32 v[226:227], v[226:227], v[222:223]
	v_pk_add_f32 v[226:227], v[226:227], v[224:225]
	v_exp_f32_e32 v218, v104
	v_exp_f32_e32 v219, v105
	v_exp_f32_e32 v220, v106
	v_exp_f32_e32 v221, v107
	v_exp_f32_e32 v222, v108
	v_exp_f32_e32 v223, v109
	v_exp_f32_e32 v224, v110
	v_exp_f32_e32 v225, v111
	v_cvt_pk_bf16_f32 v22, v218, v219
	v_cvt_pk_bf16_f32 v23, v220, v221
	v_cvt_pk_bf16_f32 v24, v222, v223
	v_cvt_pk_bf16_f32 v25, v224, v225
	v_pk_add_f32 v[226:227], v[226:227], v[218:219]
	v_pk_add_f32 v[226:227], v[226:227], v[220:221]
	v_pk_add_f32 v[226:227], v[226:227], v[222:223]
	v_pk_add_f32 v[226:227], v[226:227], v[224:225]
	s_waitcnt lgkmcnt(2)
	v_mfma_f32_32x32x16_bf16 v[48:63], v[182:185], v[8:11], v[48:63]
	ds_read_b64_tr_b16 v[26:27], v2 offset:57344
	ds_read_b64_tr_b16 v[28:29], v2 offset:57856
	ds_read_b64_tr_b16 v[84:85], v2 offset:58368
	ds_read_b64_tr_b16 v[86:87], v2 offset:58880
	s_waitcnt lgkmcnt(2)
	v_mfma_f32_32x32x16_bf16 v[32:47], v[26:29], v[8:11], v[32:47]
	v_mfma_f32_32x32x16_bf16 v[48:63], v[186:189], v[18:21], v[48:63]
	s_waitcnt lgkmcnt(0)
	v_mfma_f32_32x32x16_bf16 v[32:47], v[84:87], v[18:21], v[32:47]
	ds_read_b64_tr_b16 v[8:9], v2 offset:55296
	ds_read_b64_tr_b16 v[10:11], v2 offset:55808
	ds_read_b64_tr_b16 v[18:19], v2 offset:56320
	ds_read_b64_tr_b16 v[20:21], v2 offset:56832
	s_waitcnt lgkmcnt(2)
	v_mfma_f32_32x32x16_bf16 v[48:63], v[8:11], v[12:15], v[48:63]
	ds_read_b64_tr_b16 v[8:9], v2 offset:59392
	ds_read_b64_tr_b16 v[10:11], v2 offset:59904
	ds_read_b64_tr_b16 v[26:27], v2 offset:60416
	ds_read_b64_tr_b16 v[28:29], v2 offset:60928
	s_waitcnt lgkmcnt(2)
	v_mfma_f32_32x32x16_bf16 v[32:47], v[8:11], v[12:15], v[32:47]
	v_mfma_f32_32x32x16_bf16 v[48:63], v[18:21], v[22:25], v[48:63]
	s_waitcnt lgkmcnt(0)
	v_mfma_f32_32x32x16_bf16 v[32:47], v[26:29], v[22:25], v[32:47]
	v_add_f32_e32 v228, v226, v227
	v_add_f32_e32 v6, v6, v228
	s_add_i32 s2, s57, 64
	s_cmp_gt_i32 s2, s54
	s_cbranch_scc0 .LBB0_363

.LBB0_410:
	v_exp_f32_e32 v218, v80
	v_exp_f32_e32 v219, v81
	v_exp_f32_e32 v220, v82
	v_exp_f32_e32 v221, v83
	v_exp_f32_e32 v222, v84
	v_exp_f32_e32 v223, v85
	v_exp_f32_e32 v224, v86
	v_exp_f32_e32 v225, v87
	v_cvt_pk_bf16_f32 v8, v218, v219
	v_cvt_pk_bf16_f32 v9, v220, v221
	v_cvt_pk_bf16_f32 v10, v222, v223
	v_cvt_pk_bf16_f32 v11, v224, v225
	v_pk_add_f32 v[226:227], v[218:219], v[220:221]
	v_pk_add_f32 v[226:227], v[226:227], v[222:223]
	v_pk_add_f32 v[226:227], v[226:227], v[224:225]
	v_exp_f32_e32 v218, v88
	v_exp_f32_e32 v219, v89
	v_exp_f32_e32 v220, v90
	v_exp_f32_e32 v221, v91
	v_exp_f32_e32 v222, v92
	v_exp_f32_e32 v223, v93
	v_exp_f32_e32 v224, v94
	v_exp_f32_e32 v225, v95
	v_cvt_pk_bf16_f32 v18, v218, v219
	v_cvt_pk_bf16_f32 v19, v220, v221
	v_cvt_pk_bf16_f32 v20, v222, v223
	v_cvt_pk_bf16_f32 v21, v224, v225
	v_pk_add_f32 v[226:227], v[226:227], v[218:219]
	v_pk_add_f32 v[226:227], v[226:227], v[220:221]
	v_pk_add_f32 v[226:227], v[226:227], v[222:223]
	v_pk_add_f32 v[226:227], v[226:227], v[224:225]
	v_exp_f32_e32 v218, v96
	v_exp_f32_e32 v219, v97
	v_exp_f32_e32 v220, v98
	v_exp_f32_e32 v221, v99
	v_exp_f32_e32 v222, v100
	v_exp_f32_e32 v223, v101
	v_exp_f32_e32 v224, v102
	v_exp_f32_e32 v225, v103
	v_cvt_pk_bf16_f32 v12, v218, v219
	v_cvt_pk_bf16_f32 v13, v220, v221
	v_cvt_pk_bf16_f32 v14, v222, v223
	v_cvt_pk_bf16_f32 v15, v224, v225
	v_pk_add_f32 v[226:227], v[226:227], v[218:219]
	v_pk_add_f32 v[226:227], v[226:227], v[220:221]
	v_pk_add_f32 v[226:227], v[226:227], v[222:223]
	v_pk_add_f32 v[226:227], v[226:227], v[224:225]
	v_exp_f32_e32 v218, v104
	v_exp_f32_e32 v219, v105
	v_exp_f32_e32 v220, v106
	v_exp_f32_e32 v221, v107
	v_exp_f32_e32 v222, v108
	v_exp_f32_e32 v223, v109
	v_exp_f32_e32 v224, v110
	v_exp_f32_e32 v225, v111
	v_cvt_pk_bf16_f32 v22, v218, v219
	v_cvt_pk_bf16_f32 v23, v220, v221
	v_cvt_pk_bf16_f32 v24, v222, v223
	v_cvt_pk_bf16_f32 v25, v224, v225
	v_pk_add_f32 v[226:227], v[226:227], v[218:219]
	v_pk_add_f32 v[226:227], v[226:227], v[220:221]
	v_pk_add_f32 v[226:227], v[226:227], v[222:223]
	v_pk_add_f32 v[226:227], v[226:227], v[224:225]
	s_waitcnt lgkmcnt(2)
	v_mfma_f32_32x32x16_bf16 v[48:63], v[182:185], v[8:11], v[48:63]
	ds_read_b64_tr_b16 v[26:27], v2 offset:57344
	ds_read_b64_tr_b16 v[28:29], v2 offset:57856
	ds_read_b64_tr_b16 v[84:85], v2 offset:58368
	ds_read_b64_tr_b16 v[86:87], v2 offset:58880
	s_waitcnt lgkmcnt(2)
	v_mfma_f32_32x32x16_bf16 v[32:47], v[26:29], v[8:11], v[32:47]
	v_mfma_f32_32x32x16_bf16 v[48:63], v[186:189], v[18:21], v[48:63]
	s_waitcnt lgkmcnt(0)
	v_mfma_f32_32x32x16_bf16 v[32:47], v[84:87], v[18:21], v[32:47]
	ds_read_b64_tr_b16 v[8:9], v2 offset:55296
	ds_read_b64_tr_b16 v[10:11], v2 offset:55808
	ds_read_b64_tr_b16 v[18:19], v2 offset:56320
	ds_read_b64_tr_b16 v[20:21], v2 offset:56832
	s_waitcnt lgkmcnt(2)
	v_mfma_f32_32x32x16_bf16 v[48:63], v[8:11], v[12:15], v[48:63]
	ds_read_b64_tr_b16 v[8:9], v2 offset:59392
	ds_read_b64_tr_b16 v[10:11], v2 offset:59904
	ds_read_b64_tr_b16 v[26:27], v2 offset:60416
	ds_read_b64_tr_b16 v[28:29], v2 offset:60928
	s_waitcnt lgkmcnt(2)
	v_mfma_f32_32x32x16_bf16 v[32:47], v[8:11], v[12:15], v[32:47]
	v_mfma_f32_32x32x16_bf16 v[48:63], v[18:21], v[22:25], v[48:63]
	s_waitcnt lgkmcnt(0)
	v_mfma_f32_32x32x16_bf16 v[32:47], v[26:29], v[22:25], v[32:47]
	v_add_f32_e32 v228, v226, v227
	v_add_f32_e32 v6, v6, v228
	s_add_i32 s2, s37, 64
	s_cmp_gt_i32 s2, s28
	s_cbranch_scc0 .LBB0_401
